# final RMSNorm rewritten by hand: next 4-row group loaded while the current one is normalised and stored (counted vmcnt, global instead of flat)
# baseline (speedup 1.0000x reference)
.LBB0_1118:
	v_readlane_b32 s1, v244, 4
	v_readfirstlane_b32 s0, v194
	s_ashr_i32 s0, s0, 4
	s_and_b32 s0, s0, -4
	s_add_i32 s6, s0, s1
	s_cmp_lt_i32 s6, 0x8000
	v_readlane_b32 s22, v246, 2
	v_readlane_b32 s23, v246, 3
	s_cbranch_scc0 .LBB0_1121
	v_and_b32_e32 v18, 63, v194
	v_lshlrev_b32_e32 v16, 5, v18
	v_lshlrev_b32_e32 v17, 4, v18
	global_load_dwordx4 v[0:3], v16, s[42:43]
	global_load_dwordx4 v[4:7], v16, s[42:43] offset:16
	global_load_dwordx4 v[8:11], v16, s[42:43] offset:2048
	global_load_dwordx4 v[12:15], v16, s[42:43] offset:2064
	v_add_u32_e32 v19, 0x800, v17
	v_add_u32_e32 v20, 0x1000, v17
	v_add_u32_e32 v21, 0x1800, v17
	v_mov_b32_e32 v18, v17
	v_add_u32_e32 v23, 0x1000, v16
	v_add_u32_e32 v24, 0x2000, v16
	v_add_u32_e32 v25, 0x3000, v16
	v_mov_b32_e32 v22, v16
	v_mov_b32_e32 v26, 0
	s_lshl_b32 s0, s6, 11
	s_add_u32 s8, s46, s0
	s_addc_u32 s9, s47, 0
	s_add_u32 s8, s8, 0x4200000
	s_addc_u32 s9, s9, 0
	s_lshl_b32 s0, s6, 2
	s_add_u32 s10, s46, s0
	s_addc_u32 s11, s47, 0
	s_add_u32 s10, s10, 0x3480000
	s_addc_u32 s11, s11, 0
	s_lshl_b32 s0, s6, 12
	s_add_u32 s12, s44, s0
	s_addc_u32 s13, s45, 0
	s_lshl_b32 s14, s22, 11
	s_lshl_b32 s15, s22, 2
	s_lshl_b32 s16, s22, 12
	s_mov_b32 s17, 0x3a800000
	v_mov_b32_e32 v27, 0x358637bd
	global_load_dwordx4 v[60:63], v26, s[10:11]
	global_load_dwordx4 v[28:31], v18, s[8:9]
	global_load_dwordx4 v[32:35], v18, s[8:9] offset:1024
	global_load_dwordx4 v[36:39], v19, s[8:9]
	global_load_dwordx4 v[40:43], v19, s[8:9] offset:1024
	global_load_dwordx4 v[44:47], v20, s[8:9]
	global_load_dwordx4 v[48:51], v20, s[8:9] offset:1024
	global_load_dwordx4 v[52:55], v21, s[8:9]
	global_load_dwordx4 v[56:59], v21, s[8:9] offset:1024
	s_add_i32 s7, s6, s22
	s_cmp_lt_i32 s7, 0x8000
	s_cbranch_scc0 .Lfin_noadv_0
	s_add_u32 s8, s8, s14
	s_addc_u32 s9, s9, 0
	s_add_u32 s10, s10, s15
	s_addc_u32 s11, s11, 0
.Lfin_noadv_0:
	global_load_dwordx4 v[96:99], v26, s[10:11]
	global_load_dwordx4 v[64:67], v18, s[8:9]
	global_load_dwordx4 v[68:71], v18, s[8:9] offset:1024
	global_load_dwordx4 v[72:75], v19, s[8:9]
	global_load_dwordx4 v[76:79], v19, s[8:9] offset:1024
	global_load_dwordx4 v[80:83], v20, s[8:9]
	global_load_dwordx4 v[84:87], v20, s[8:9] offset:1024
	global_load_dwordx4 v[88:91], v21, s[8:9]
	global_load_dwordx4 v[92:95], v21, s[8:9] offset:1024
	s_waitcnt vmcnt(9)
	v_fmamk_f32 v60, v60, 0x3a800000, v27
	v_fmamk_f32 v61, v61, 0x3a800000, v27
	v_fmamk_f32 v62, v62, 0x3a800000, v27
	v_fmamk_f32 v63, v63, 0x3a800000, v27
	v_rsq_f32_e32 v60, v60
	v_rsq_f32_e32 v61, v61
	v_rsq_f32_e32 v62, v62
	v_rsq_f32_e32 v63, v63
	s_nop 0
	v_lshlrev_b32_e32 v100, 16, v28
	v_and_b32_e32 v101, 0xffff0000, v28
	v_lshlrev_b32_e32 v102, 16, v29
	v_and_b32_e32 v103, 0xffff0000, v29
	v_lshlrev_b32_e32 v104, 16, v30
	v_and_b32_e32 v105, 0xffff0000, v30
	v_lshlrev_b32_e32 v106, 16, v31
	v_and_b32_e32 v107, 0xffff0000, v31
	v_pk_mul_f32 v[100:101], v[60:61], v[100:101] op_sel_hi:[0,1]
	v_pk_mul_f32 v[102:103], v[60:61], v[102:103] op_sel_hi:[0,1]
	v_pk_mul_f32 v[104:105], v[60:61], v[104:105] op_sel_hi:[0,1]
	v_pk_mul_f32 v[106:107], v[60:61], v[106:107] op_sel_hi:[0,1]
	v_pk_mul_f32 v[100:101], v[100:101], v[0:1]
	v_pk_mul_f32 v[102:103], v[102:103], v[2:3]
	v_pk_mul_f32 v[104:105], v[104:105], v[4:5]
	v_pk_mul_f32 v[106:107], v[106:107], v[6:7]
	global_store_dwordx4 v22, v[100:103], s[12:13]
	global_store_dwordx4 v22, v[104:107], s[12:13] offset:16
	v_lshlrev_b32_e32 v108, 16, v32
	v_and_b32_e32 v109, 0xffff0000, v32
	v_lshlrev_b32_e32 v110, 16, v33
	v_and_b32_e32 v111, 0xffff0000, v33
	v_lshlrev_b32_e32 v112, 16, v34
	v_and_b32_e32 v113, 0xffff0000, v34
	v_lshlrev_b32_e32 v114, 16, v35
	v_and_b32_e32 v115, 0xffff0000, v35
	v_pk_mul_f32 v[108:109], v[60:61], v[108:109] op_sel_hi:[0,1]
	v_pk_mul_f32 v[110:111], v[60:61], v[110:111] op_sel_hi:[0,1]
	v_pk_mul_f32 v[112:113], v[60:61], v[112:113] op_sel_hi:[0,1]
	v_pk_mul_f32 v[114:115], v[60:61], v[114:115] op_sel_hi:[0,1]
	v_pk_mul_f32 v[108:109], v[108:109], v[8:9]
	v_pk_mul_f32 v[110:111], v[110:111], v[10:11]
	v_pk_mul_f32 v[112:113], v[112:113], v[12:13]
	v_pk_mul_f32 v[114:115], v[114:115], v[14:15]
	global_store_dwordx4 v22, v[108:111], s[12:13] offset:2048
	global_store_dwordx4 v22, v[112:115], s[12:13] offset:2064
	v_lshlrev_b32_e32 v100, 16, v36
	v_and_b32_e32 v101, 0xffff0000, v36
	v_lshlrev_b32_e32 v102, 16, v37
	v_and_b32_e32 v103, 0xffff0000, v37
	v_lshlrev_b32_e32 v104, 16, v38
	v_and_b32_e32 v105, 0xffff0000, v38
	v_lshlrev_b32_e32 v106, 16, v39
	v_and_b32_e32 v107, 0xffff0000, v39
	v_pk_mul_f32 v[100:101], v[60:61], v[100:101] op_sel:[1,0] op_sel_hi:[1,1]
	v_pk_mul_f32 v[102:103], v[60:61], v[102:103] op_sel:[1,0] op_sel_hi:[1,1]
	v_pk_mul_f32 v[104:105], v[60:61], v[104:105] op_sel:[1,0] op_sel_hi:[1,1]
	v_pk_mul_f32 v[106:107], v[60:61], v[106:107] op_sel:[1,0] op_sel_hi:[1,1]
	v_pk_mul_f32 v[100:101], v[100:101], v[0:1]
	v_pk_mul_f32 v[102:103], v[102:103], v[2:3]
	v_pk_mul_f32 v[104:105], v[104:105], v[4:5]
	v_pk_mul_f32 v[106:107], v[106:107], v[6:7]
	global_store_dwordx4 v23, v[100:103], s[12:13]
	global_store_dwordx4 v23, v[104:107], s[12:13] offset:16
	v_lshlrev_b32_e32 v108, 16, v40
	v_and_b32_e32 v109, 0xffff0000, v40
	v_lshlrev_b32_e32 v110, 16, v41
	v_and_b32_e32 v111, 0xffff0000, v41
	v_lshlrev_b32_e32 v112, 16, v42
	v_and_b32_e32 v113, 0xffff0000, v42
	v_lshlrev_b32_e32 v114, 16, v43
	v_and_b32_e32 v115, 0xffff0000, v43
	v_pk_mul_f32 v[108:109], v[60:61], v[108:109] op_sel:[1,0] op_sel_hi:[1,1]
	v_pk_mul_f32 v[110:111], v[60:61], v[110:111] op_sel:[1,0] op_sel_hi:[1,1]
	v_pk_mul_f32 v[112:113], v[60:61], v[112:113] op_sel:[1,0] op_sel_hi:[1,1]
	v_pk_mul_f32 v[114:115], v[60:61], v[114:115] op_sel:[1,0] op_sel_hi:[1,1]
	v_pk_mul_f32 v[108:109], v[108:109], v[8:9]
	v_pk_mul_f32 v[110:111], v[110:111], v[10:11]
	v_pk_mul_f32 v[112:113], v[112:113], v[12:13]
	v_pk_mul_f32 v[114:115], v[114:115], v[14:15]
	global_store_dwordx4 v23, v[108:111], s[12:13] offset:2048
	global_store_dwordx4 v23, v[112:115], s[12:13] offset:2064
	v_lshlrev_b32_e32 v100, 16, v44
	v_and_b32_e32 v101, 0xffff0000, v44
	v_lshlrev_b32_e32 v102, 16, v45
	v_and_b32_e32 v103, 0xffff0000, v45
	v_lshlrev_b32_e32 v104, 16, v46
	v_and_b32_e32 v105, 0xffff0000, v46
	v_lshlrev_b32_e32 v106, 16, v47
	v_and_b32_e32 v107, 0xffff0000, v47
	v_pk_mul_f32 v[100:101], v[62:63], v[100:101] op_sel_hi:[0,1]
	v_pk_mul_f32 v[102:103], v[62:63], v[102:103] op_sel_hi:[0,1]
	v_pk_mul_f32 v[104:105], v[62:63], v[104:105] op_sel_hi:[0,1]
	v_pk_mul_f32 v[106:107], v[62:63], v[106:107] op_sel_hi:[0,1]
	v_pk_mul_f32 v[100:101], v[100:101], v[0:1]
	v_pk_mul_f32 v[102:103], v[102:103], v[2:3]
	v_pk_mul_f32 v[104:105], v[104:105], v[4:5]
	v_pk_mul_f32 v[106:107], v[106:107], v[6:7]
	global_store_dwordx4 v24, v[100:103], s[12:13]
	global_store_dwordx4 v24, v[104:107], s[12:13] offset:16
	v_lshlrev_b32_e32 v108, 16, v48
	v_and_b32_e32 v109, 0xffff0000, v48
	v_lshlrev_b32_e32 v110, 16, v49
	v_and_b32_e32 v111, 0xffff0000, v49
	v_lshlrev_b32_e32 v112, 16, v50
	v_and_b32_e32 v113, 0xffff0000, v50
	v_lshlrev_b32_e32 v114, 16, v51
	v_and_b32_e32 v115, 0xffff0000, v51
	v_pk_mul_f32 v[108:109], v[62:63], v[108:109] op_sel_hi:[0,1]
	v_pk_mul_f32 v[110:111], v[62:63], v[110:111] op_sel_hi:[0,1]
	v_pk_mul_f32 v[112:113], v[62:63], v[112:113] op_sel_hi:[0,1]
	v_pk_mul_f32 v[114:115], v[62:63], v[114:115] op_sel_hi:[0,1]
	v_pk_mul_f32 v[108:109], v[108:109], v[8:9]
	v_pk_mul_f32 v[110:111], v[110:111], v[10:11]
	v_pk_mul_f32 v[112:113], v[112:113], v[12:13]
	v_pk_mul_f32 v[114:115], v[114:115], v[14:15]
	global_store_dwordx4 v24, v[108:111], s[12:13] offset:2048
	global_store_dwordx4 v24, v[112:115], s[12:13] offset:2064
	v_lshlrev_b32_e32 v100, 16, v52
	v_and_b32_e32 v101, 0xffff0000, v52
	v_lshlrev_b32_e32 v102, 16, v53
	v_and_b32_e32 v103, 0xffff0000, v53
	v_lshlrev_b32_e32 v104, 16, v54
	v_and_b32_e32 v105, 0xffff0000, v54
	v_lshlrev_b32_e32 v106, 16, v55
	v_and_b32_e32 v107, 0xffff0000, v55
	v_pk_mul_f32 v[100:101], v[62:63], v[100:101] op_sel:[1,0] op_sel_hi:[1,1]
	v_pk_mul_f32 v[102:103], v[62:63], v[102:103] op_sel:[1,0] op_sel_hi:[1,1]
	v_pk_mul_f32 v[104:105], v[62:63], v[104:105] op_sel:[1,0] op_sel_hi:[1,1]
	v_pk_mul_f32 v[106:107], v[62:63], v[106:107] op_sel:[1,0] op_sel_hi:[1,1]
	v_pk_mul_f32 v[100:101], v[100:101], v[0:1]
	v_pk_mul_f32 v[102:103], v[102:103], v[2:3]
	v_pk_mul_f32 v[104:105], v[104:105], v[4:5]
	v_pk_mul_f32 v[106:107], v[106:107], v[6:7]
	global_store_dwordx4 v25, v[100:103], s[12:13]
	global_store_dwordx4 v25, v[104:107], s[12:13] offset:16
	v_lshlrev_b32_e32 v108, 16, v56
	v_and_b32_e32 v109, 0xffff0000, v56
	v_lshlrev_b32_e32 v110, 16, v57
	v_and_b32_e32 v111, 0xffff0000, v57
	v_lshlrev_b32_e32 v112, 16, v58
	v_and_b32_e32 v113, 0xffff0000, v58
	v_lshlrev_b32_e32 v114, 16, v59
	v_and_b32_e32 v115, 0xffff0000, v59
	v_pk_mul_f32 v[108:109], v[62:63], v[108:109] op_sel:[1,0] op_sel_hi:[1,1]
	v_pk_mul_f32 v[110:111], v[62:63], v[110:111] op_sel:[1,0] op_sel_hi:[1,1]
	v_pk_mul_f32 v[112:113], v[62:63], v[112:113] op_sel:[1,0] op_sel_hi:[1,1]
	v_pk_mul_f32 v[114:115], v[62:63], v[114:115] op_sel:[1,0] op_sel_hi:[1,1]
	v_pk_mul_f32 v[108:109], v[108:109], v[8:9]
	v_pk_mul_f32 v[110:111], v[110:111], v[10:11]
	v_pk_mul_f32 v[112:113], v[112:113], v[12:13]
	v_pk_mul_f32 v[114:115], v[114:115], v[14:15]
	global_store_dwordx4 v25, v[108:111], s[12:13] offset:2048
	global_store_dwordx4 v25, v[112:115], s[12:13] offset:2064
	s_add_u32 s12, s12, s16
	s_addc_u32 s13, s13, 0
	s_add_i32 s6, s6, s22
	s_cmp_lt_i32 s6, 0x8000
	s_cbranch_scc0 .Lfin_done
.Lfin_loop:
	s_add_i32 s7, s6, s22
	s_cmp_lt_i32 s7, 0x8000
	s_cbranch_scc0 .Lfin_noadv_1
	s_add_u32 s8, s8, s14
	s_addc_u32 s9, s9, 0
	s_add_u32 s10, s10, s15
	s_addc_u32 s11, s11, 0
.Lfin_noadv_1:
	global_load_dwordx4 v[60:63], v26, s[10:11]
	global_load_dwordx4 v[28:31], v18, s[8:9]
	global_load_dwordx4 v[32:35], v18, s[8:9] offset:1024
	global_load_dwordx4 v[36:39], v19, s[8:9]
	global_load_dwordx4 v[40:43], v19, s[8:9] offset:1024
	global_load_dwordx4 v[44:47], v20, s[8:9]
	global_load_dwordx4 v[48:51], v20, s[8:9] offset:1024
	global_load_dwordx4 v[52:55], v21, s[8:9]
	global_load_dwordx4 v[56:59], v21, s[8:9] offset:1024
	s_waitcnt vmcnt(25)
	v_fmamk_f32 v96, v96, 0x3a800000, v27
	v_fmamk_f32 v97, v97, 0x3a800000, v27
	v_fmamk_f32 v98, v98, 0x3a800000, v27
	v_fmamk_f32 v99, v99, 0x3a800000, v27
	v_rsq_f32_e32 v96, v96
	v_rsq_f32_e32 v97, v97
	v_rsq_f32_e32 v98, v98
	v_rsq_f32_e32 v99, v99
	s_nop 0
	v_lshlrev_b32_e32 v100, 16, v64
	v_and_b32_e32 v101, 0xffff0000, v64
	v_lshlrev_b32_e32 v102, 16, v65
	v_and_b32_e32 v103, 0xffff0000, v65
	v_lshlrev_b32_e32 v104, 16, v66
	v_and_b32_e32 v105, 0xffff0000, v66
	v_lshlrev_b32_e32 v106, 16, v67
	v_and_b32_e32 v107, 0xffff0000, v67
	v_pk_mul_f32 v[100:101], v[96:97], v[100:101] op_sel_hi:[0,1]
	v_pk_mul_f32 v[102:103], v[96:97], v[102:103] op_sel_hi:[0,1]
	v_pk_mul_f32 v[104:105], v[96:97], v[104:105] op_sel_hi:[0,1]
	v_pk_mul_f32 v[106:107], v[96:97], v[106:107] op_sel_hi:[0,1]
	v_pk_mul_f32 v[100:101], v[100:101], v[0:1]
	v_pk_mul_f32 v[102:103], v[102:103], v[2:3]
	v_pk_mul_f32 v[104:105], v[104:105], v[4:5]
	v_pk_mul_f32 v[106:107], v[106:107], v[6:7]
	global_store_dwordx4 v22, v[100:103], s[12:13]
	global_store_dwordx4 v22, v[104:107], s[12:13] offset:16
	v_lshlrev_b32_e32 v108, 16, v68
	v_and_b32_e32 v109, 0xffff0000, v68
	v_lshlrev_b32_e32 v110, 16, v69
	v_and_b32_e32 v111, 0xffff0000, v69
	v_lshlrev_b32_e32 v112, 16, v70
	v_and_b32_e32 v113, 0xffff0000, v70
	v_lshlrev_b32_e32 v114, 16, v71
	v_and_b32_e32 v115, 0xffff0000, v71
	v_pk_mul_f32 v[108:109], v[96:97], v[108:109] op_sel_hi:[0,1]
	v_pk_mul_f32 v[110:111], v[96:97], v[110:111] op_sel_hi:[0,1]
	v_pk_mul_f32 v[112:113], v[96:97], v[112:113] op_sel_hi:[0,1]
	v_pk_mul_f32 v[114:115], v[96:97], v[114:115] op_sel_hi:[0,1]
	v_pk_mul_f32 v[108:109], v[108:109], v[8:9]
	v_pk_mul_f32 v[110:111], v[110:111], v[10:11]
	v_pk_mul_f32 v[112:113], v[112:113], v[12:13]
	v_pk_mul_f32 v[114:115], v[114:115], v[14:15]
	global_store_dwordx4 v22, v[108:111], s[12:13] offset:2048
	global_store_dwordx4 v22, v[112:115], s[12:13] offset:2064
	v_lshlrev_b32_e32 v100, 16, v72
	v_and_b32_e32 v101, 0xffff0000, v72
	v_lshlrev_b32_e32 v102, 16, v73
	v_and_b32_e32 v103, 0xffff0000, v73
	v_lshlrev_b32_e32 v104, 16, v74
	v_and_b32_e32 v105, 0xffff0000, v74
	v_lshlrev_b32_e32 v106, 16, v75
	v_and_b32_e32 v107, 0xffff0000, v75
	v_pk_mul_f32 v[100:101], v[96:97], v[100:101] op_sel:[1,0] op_sel_hi:[1,1]
	v_pk_mul_f32 v[102:103], v[96:97], v[102:103] op_sel:[1,0] op_sel_hi:[1,1]
	v_pk_mul_f32 v[104:105], v[96:97], v[104:105] op_sel:[1,0] op_sel_hi:[1,1]
	v_pk_mul_f32 v[106:107], v[96:97], v[106:107] op_sel:[1,0] op_sel_hi:[1,1]
	v_pk_mul_f32 v[100:101], v[100:101], v[0:1]
	v_pk_mul_f32 v[102:103], v[102:103], v[2:3]
	v_pk_mul_f32 v[104:105], v[104:105], v[4:5]
	v_pk_mul_f32 v[106:107], v[106:107], v[6:7]
	global_store_dwordx4 v23, v[100:103], s[12:13]
	global_store_dwordx4 v23, v[104:107], s[12:13] offset:16
	v_lshlrev_b32_e32 v108, 16, v76
	v_and_b32_e32 v109, 0xffff0000, v76
	v_lshlrev_b32_e32 v110, 16, v77
	v_and_b32_e32 v111, 0xffff0000, v77
	v_lshlrev_b32_e32 v112, 16, v78
	v_and_b32_e32 v113, 0xffff0000, v78
	v_lshlrev_b32_e32 v114, 16, v79
	v_and_b32_e32 v115, 0xffff0000, v79
	v_pk_mul_f32 v[108:109], v[96:97], v[108:109] op_sel:[1,0] op_sel_hi:[1,1]
	v_pk_mul_f32 v[110:111], v[96:97], v[110:111] op_sel:[1,0] op_sel_hi:[1,1]
	v_pk_mul_f32 v[112:113], v[96:97], v[112:113] op_sel:[1,0] op_sel_hi:[1,1]
	v_pk_mul_f32 v[114:115], v[96:97], v[114:115] op_sel:[1,0] op_sel_hi:[1,1]
	v_pk_mul_f32 v[108:109], v[108:109], v[8:9]
	v_pk_mul_f32 v[110:111], v[110:111], v[10:11]
	v_pk_mul_f32 v[112:113], v[112:113], v[12:13]
	v_pk_mul_f32 v[114:115], v[114:115], v[14:15]
	global_store_dwordx4 v23, v[108:111], s[12:13] offset:2048
	global_store_dwordx4 v23, v[112:115], s[12:13] offset:2064
	v_lshlrev_b32_e32 v100, 16, v80
	v_and_b32_e32 v101, 0xffff0000, v80
	v_lshlrev_b32_e32 v102, 16, v81
	v_and_b32_e32 v103, 0xffff0000, v81
	v_lshlrev_b32_e32 v104, 16, v82
	v_and_b32_e32 v105, 0xffff0000, v82
	v_lshlrev_b32_e32 v106, 16, v83
	v_and_b32_e32 v107, 0xffff0000, v83
	v_pk_mul_f32 v[100:101], v[98:99], v[100:101] op_sel_hi:[0,1]
	v_pk_mul_f32 v[102:103], v[98:99], v[102:103] op_sel_hi:[0,1]
	v_pk_mul_f32 v[104:105], v[98:99], v[104:105] op_sel_hi:[0,1]
	v_pk_mul_f32 v[106:107], v[98:99], v[106:107] op_sel_hi:[0,1]
	v_pk_mul_f32 v[100:101], v[100:101], v[0:1]
	v_pk_mul_f32 v[102:103], v[102:103], v[2:3]
	v_pk_mul_f32 v[104:105], v[104:105], v[4:5]
	v_pk_mul_f32 v[106:107], v[106:107], v[6:7]
	global_store_dwordx4 v24, v[100:103], s[12:13]
	global_store_dwordx4 v24, v[104:107], s[12:13] offset:16
	v_lshlrev_b32_e32 v108, 16, v84
	v_and_b32_e32 v109, 0xffff0000, v84
	v_lshlrev_b32_e32 v110, 16, v85
	v_and_b32_e32 v111, 0xffff0000, v85
	v_lshlrev_b32_e32 v112, 16, v86
	v_and_b32_e32 v113, 0xffff0000, v86
	v_lshlrev_b32_e32 v114, 16, v87
	v_and_b32_e32 v115, 0xffff0000, v87
	v_pk_mul_f32 v[108:109], v[98:99], v[108:109] op_sel_hi:[0,1]
	v_pk_mul_f32 v[110:111], v[98:99], v[110:111] op_sel_hi:[0,1]
	v_pk_mul_f32 v[112:113], v[98:99], v[112:113] op_sel_hi:[0,1]
	v_pk_mul_f32 v[114:115], v[98:99], v[114:115] op_sel_hi:[0,1]
	v_pk_mul_f32 v[108:109], v[108:109], v[8:9]
	v_pk_mul_f32 v[110:111], v[110:111], v[10:11]
	v_pk_mul_f32 v[112:113], v[112:113], v[12:13]
	v_pk_mul_f32 v[114:115], v[114:115], v[14:15]
	global_store_dwordx4 v24, v[108:111], s[12:13] offset:2048
	global_store_dwordx4 v24, v[112:115], s[12:13] offset:2064
	v_lshlrev_b32_e32 v100, 16, v88
	v_and_b32_e32 v101, 0xffff0000, v88
	v_lshlrev_b32_e32 v102, 16, v89
	v_and_b32_e32 v103, 0xffff0000, v89
	v_lshlrev_b32_e32 v104, 16, v90
	v_and_b32_e32 v105, 0xffff0000, v90
	v_lshlrev_b32_e32 v106, 16, v91
	v_and_b32_e32 v107, 0xffff0000, v91
	v_pk_mul_f32 v[100:101], v[98:99], v[100:101] op_sel:[1,0] op_sel_hi:[1,1]
	v_pk_mul_f32 v[102:103], v[98:99], v[102:103] op_sel:[1,0] op_sel_hi:[1,1]
	v_pk_mul_f32 v[104:105], v[98:99], v[104:105] op_sel:[1,0] op_sel_hi:[1,1]
	v_pk_mul_f32 v[106:107], v[98:99], v[106:107] op_sel:[1,0] op_sel_hi:[1,1]
	v_pk_mul_f32 v[100:101], v[100:101], v[0:1]
	v_pk_mul_f32 v[102:103], v[102:103], v[2:3]
	v_pk_mul_f32 v[104:105], v[104:105], v[4:5]
	v_pk_mul_f32 v[106:107], v[106:107], v[6:7]
	global_store_dwordx4 v25, v[100:103], s[12:13]
	global_store_dwordx4 v25, v[104:107], s[12:13] offset:16
	v_lshlrev_b32_e32 v108, 16, v92
	v_and_b32_e32 v109, 0xffff0000, v92
	v_lshlrev_b32_e32 v110, 16, v93
	v_and_b32_e32 v111, 0xffff0000, v93
	v_lshlrev_b32_e32 v112, 16, v94
	v_and_b32_e32 v113, 0xffff0000, v94
	v_lshlrev_b32_e32 v114, 16, v95
	v_and_b32_e32 v115, 0xffff0000, v95
	v_pk_mul_f32 v[108:109], v[98:99], v[108:109] op_sel:[1,0] op_sel_hi:[1,1]
	v_pk_mul_f32 v[110:111], v[98:99], v[110:111] op_sel:[1,0] op_sel_hi:[1,1]
	v_pk_mul_f32 v[112:113], v[98:99], v[112:113] op_sel:[1,0] op_sel_hi:[1,1]
	v_pk_mul_f32 v[114:115], v[98:99], v[114:115] op_sel:[1,0] op_sel_hi:[1,1]
	v_pk_mul_f32 v[108:109], v[108:109], v[8:9]
	v_pk_mul_f32 v[110:111], v[110:111], v[10:11]
	v_pk_mul_f32 v[112:113], v[112:113], v[12:13]
	v_pk_mul_f32 v[114:115], v[114:115], v[14:15]
	global_store_dwordx4 v25, v[108:111], s[12:13] offset:2048
	global_store_dwordx4 v25, v[112:115], s[12:13] offset:2064
	s_add_u32 s12, s12, s16
	s_addc_u32 s13, s13, 0
	s_add_i32 s6, s6, s22
	s_cmp_lt_i32 s6, 0x8000
	s_cbranch_scc0 .Lfin_done
	s_add_i32 s7, s6, s22
	s_cmp_lt_i32 s7, 0x8000
	s_cbranch_scc0 .Lfin_noadv_2
	s_add_u32 s8, s8, s14
	s_addc_u32 s9, s9, 0
	s_add_u32 s10, s10, s15
	s_addc_u32 s11, s11, 0
.Lfin_noadv_2:
	global_load_dwordx4 v[96:99], v26, s[10:11]
	global_load_dwordx4 v[64:67], v18, s[8:9]
	global_load_dwordx4 v[68:71], v18, s[8:9] offset:1024
	global_load_dwordx4 v[72:75], v19, s[8:9]
	global_load_dwordx4 v[76:79], v19, s[8:9] offset:1024
	global_load_dwordx4 v[80:83], v20, s[8:9]
	global_load_dwordx4 v[84:87], v20, s[8:9] offset:1024
	global_load_dwordx4 v[88:91], v21, s[8:9]
	global_load_dwordx4 v[92:95], v21, s[8:9] offset:1024
	s_waitcnt vmcnt(25)
	v_fmamk_f32 v60, v60, 0x3a800000, v27
	v_fmamk_f32 v61, v61, 0x3a800000, v27
	v_fmamk_f32 v62, v62, 0x3a800000, v27
	v_fmamk_f32 v63, v63, 0x3a800000, v27
	v_rsq_f32_e32 v60, v60
	v_rsq_f32_e32 v61, v61
	v_rsq_f32_e32 v62, v62
	v_rsq_f32_e32 v63, v63
	s_nop 0
	v_lshlrev_b32_e32 v100, 16, v28
	v_and_b32_e32 v101, 0xffff0000, v28
	v_lshlrev_b32_e32 v102, 16, v29
	v_and_b32_e32 v103, 0xffff0000, v29
	v_lshlrev_b32_e32 v104, 16, v30
	v_and_b32_e32 v105, 0xffff0000, v30
	v_lshlrev_b32_e32 v106, 16, v31
	v_and_b32_e32 v107, 0xffff0000, v31
	v_pk_mul_f32 v[100:101], v[60:61], v[100:101] op_sel_hi:[0,1]
	v_pk_mul_f32 v[102:103], v[60:61], v[102:103] op_sel_hi:[0,1]
	v_pk_mul_f32 v[104:105], v[60:61], v[104:105] op_sel_hi:[0,1]
	v_pk_mul_f32 v[106:107], v[60:61], v[106:107] op_sel_hi:[0,1]
	v_pk_mul_f32 v[100:101], v[100:101], v[0:1]
	v_pk_mul_f32 v[102:103], v[102:103], v[2:3]
	v_pk_mul_f32 v[104:105], v[104:105], v[4:5]
	v_pk_mul_f32 v[106:107], v[106:107], v[6:7]
	global_store_dwordx4 v22, v[100:103], s[12:13]
	global_store_dwordx4 v22, v[104:107], s[12:13] offset:16
	v_lshlrev_b32_e32 v108, 16, v32
	v_and_b32_e32 v109, 0xffff0000, v32
	v_lshlrev_b32_e32 v110, 16, v33
	v_and_b32_e32 v111, 0xffff0000, v33
	v_lshlrev_b32_e32 v112, 16, v34
	v_and_b32_e32 v113, 0xffff0000, v34
	v_lshlrev_b32_e32 v114, 16, v35
	v_and_b32_e32 v115, 0xffff0000, v35
	v_pk_mul_f32 v[108:109], v[60:61], v[108:109] op_sel_hi:[0,1]
	v_pk_mul_f32 v[110:111], v[60:61], v[110:111] op_sel_hi:[0,1]
	v_pk_mul_f32 v[112:113], v[60:61], v[112:113] op_sel_hi:[0,1]
	v_pk_mul_f32 v[114:115], v[60:61], v[114:115] op_sel_hi:[0,1]
	v_pk_mul_f32 v[108:109], v[108:109], v[8:9]
	v_pk_mul_f32 v[110:111], v[110:111], v[10:11]
	v_pk_mul_f32 v[112:113], v[112:113], v[12:13]
	v_pk_mul_f32 v[114:115], v[114:115], v[14:15]
	global_store_dwordx4 v22, v[108:111], s[12:13] offset:2048
	global_store_dwordx4 v22, v[112:115], s[12:13] offset:2064
	v_lshlrev_b32_e32 v100, 16, v36
	v_and_b32_e32 v101, 0xffff0000, v36
	v_lshlrev_b32_e32 v102, 16, v37
	v_and_b32_e32 v103, 0xffff0000, v37
	v_lshlrev_b32_e32 v104, 16, v38
	v_and_b32_e32 v105, 0xffff0000, v38
	v_lshlrev_b32_e32 v106, 16, v39
	v_and_b32_e32 v107, 0xffff0000, v39
	v_pk_mul_f32 v[100:101], v[60:61], v[100:101] op_sel:[1,0] op_sel_hi:[1,1]
	v_pk_mul_f32 v[102:103], v[60:61], v[102:103] op_sel:[1,0] op_sel_hi:[1,1]
	v_pk_mul_f32 v[104:105], v[60:61], v[104:105] op_sel:[1,0] op_sel_hi:[1,1]
	v_pk_mul_f32 v[106:107], v[60:61], v[106:107] op_sel:[1,0] op_sel_hi:[1,1]
	v_pk_mul_f32 v[100:101], v[100:101], v[0:1]
	v_pk_mul_f32 v[102:103], v[102:103], v[2:3]
	v_pk_mul_f32 v[104:105], v[104:105], v[4:5]
	v_pk_mul_f32 v[106:107], v[106:107], v[6:7]
	global_store_dwordx4 v23, v[100:103], s[12:13]
	global_store_dwordx4 v23, v[104:107], s[12:13] offset:16
	v_lshlrev_b32_e32 v108, 16, v40
	v_and_b32_e32 v109, 0xffff0000, v40
	v_lshlrev_b32_e32 v110, 16, v41
	v_and_b32_e32 v111, 0xffff0000, v41
	v_lshlrev_b32_e32 v112, 16, v42
	v_and_b32_e32 v113, 0xffff0000, v42
	v_lshlrev_b32_e32 v114, 16, v43
	v_and_b32_e32 v115, 0xffff0000, v43
	v_pk_mul_f32 v[108:109], v[60:61], v[108:109] op_sel:[1,0] op_sel_hi:[1,1]
	v_pk_mul_f32 v[110:111], v[60:61], v[110:111] op_sel:[1,0] op_sel_hi:[1,1]
	v_pk_mul_f32 v[112:113], v[60:61], v[112:113] op_sel:[1,0] op_sel_hi:[1,1]
	v_pk_mul_f32 v[114:115], v[60:61], v[114:115] op_sel:[1,0] op_sel_hi:[1,1]
	v_pk_mul_f32 v[108:109], v[108:109], v[8:9]
	v_pk_mul_f32 v[110:111], v[110:111], v[10:11]
	v_pk_mul_f32 v[112:113], v[112:113], v[12:13]
	v_pk_mul_f32 v[114:115], v[114:115], v[14:15]
	global_store_dwordx4 v23, v[108:111], s[12:13] offset:2048
	global_store_dwordx4 v23, v[112:115], s[12:13] offset:2064
	v_lshlrev_b32_e32 v100, 16, v44
	v_and_b32_e32 v101, 0xffff0000, v44
	v_lshlrev_b32_e32 v102, 16, v45
	v_and_b32_e32 v103, 0xffff0000, v45
	v_lshlrev_b32_e32 v104, 16, v46
	v_and_b32_e32 v105, 0xffff0000, v46
	v_lshlrev_b32_e32 v106, 16, v47
	v_and_b32_e32 v107, 0xffff0000, v47
	v_pk_mul_f32 v[100:101], v[62:63], v[100:101] op_sel_hi:[0,1]
	v_pk_mul_f32 v[102:103], v[62:63], v[102:103] op_sel_hi:[0,1]
	v_pk_mul_f32 v[104:105], v[62:63], v[104:105] op_sel_hi:[0,1]
	v_pk_mul_f32 v[106:107], v[62:63], v[106:107] op_sel_hi:[0,1]
	v_pk_mul_f32 v[100:101], v[100:101], v[0:1]
	v_pk_mul_f32 v[102:103], v[102:103], v[2:3]
	v_pk_mul_f32 v[104:105], v[104:105], v[4:5]
	v_pk_mul_f32 v[106:107], v[106:107], v[6:7]
	global_store_dwordx4 v24, v[100:103], s[12:13]
	global_store_dwordx4 v24, v[104:107], s[12:13] offset:16
	v_lshlrev_b32_e32 v108, 16, v48
	v_and_b32_e32 v109, 0xffff0000, v48
	v_lshlrev_b32_e32 v110, 16, v49
	v_and_b32_e32 v111, 0xffff0000, v49
	v_lshlrev_b32_e32 v112, 16, v50
	v_and_b32_e32 v113, 0xffff0000, v50
	v_lshlrev_b32_e32 v114, 16, v51
	v_and_b32_e32 v115, 0xffff0000, v51
	v_pk_mul_f32 v[108:109], v[62:63], v[108:109] op_sel_hi:[0,1]
	v_pk_mul_f32 v[110:111], v[62:63], v[110:111] op_sel_hi:[0,1]
	v_pk_mul_f32 v[112:113], v[62:63], v[112:113] op_sel_hi:[0,1]
	v_pk_mul_f32 v[114:115], v[62:63], v[114:115] op_sel_hi:[0,1]
	v_pk_mul_f32 v[108:109], v[108:109], v[8:9]
	v_pk_mul_f32 v[110:111], v[110:111], v[10:11]
	v_pk_mul_f32 v[112:113], v[112:113], v[12:13]
	v_pk_mul_f32 v[114:115], v[114:115], v[14:15]
	global_store_dwordx4 v24, v[108:111], s[12:13] offset:2048
	global_store_dwordx4 v24, v[112:115], s[12:13] offset:2064
	v_lshlrev_b32_e32 v100, 16, v52
	v_and_b32_e32 v101, 0xffff0000, v52
	v_lshlrev_b32_e32 v102, 16, v53
	v_and_b32_e32 v103, 0xffff0000, v53
	v_lshlrev_b32_e32 v104, 16, v54
	v_and_b32_e32 v105, 0xffff0000, v54
	v_lshlrev_b32_e32 v106, 16, v55
	v_and_b32_e32 v107, 0xffff0000, v55
	v_pk_mul_f32 v[100:101], v[62:63], v[100:101] op_sel:[1,0] op_sel_hi:[1,1]
	v_pk_mul_f32 v[102:103], v[62:63], v[102:103] op_sel:[1,0] op_sel_hi:[1,1]
	v_pk_mul_f32 v[104:105], v[62:63], v[104:105] op_sel:[1,0] op_sel_hi:[1,1]
	v_pk_mul_f32 v[106:107], v[62:63], v[106:107] op_sel:[1,0] op_sel_hi:[1,1]
	v_pk_mul_f32 v[100:101], v[100:101], v[0:1]
	v_pk_mul_f32 v[102:103], v[102:103], v[2:3]
	v_pk_mul_f32 v[104:105], v[104:105], v[4:5]
	v_pk_mul_f32 v[106:107], v[106:107], v[6:7]
	global_store_dwordx4 v25, v[100:103], s[12:13]
	global_store_dwordx4 v25, v[104:107], s[12:13] offset:16
	v_lshlrev_b32_e32 v108, 16, v56
	v_and_b32_e32 v109, 0xffff0000, v56
	v_lshlrev_b32_e32 v110, 16, v57
	v_and_b32_e32 v111, 0xffff0000, v57
	v_lshlrev_b32_e32 v112, 16, v58
	v_and_b32_e32 v113, 0xffff0000, v58
	v_lshlrev_b32_e32 v114, 16, v59
	v_and_b32_e32 v115, 0xffff0000, v59
	v_pk_mul_f32 v[108:109], v[62:63], v[108:109] op_sel:[1,0] op_sel_hi:[1,1]
	v_pk_mul_f32 v[110:111], v[62:63], v[110:111] op_sel:[1,0] op_sel_hi:[1,1]
	v_pk_mul_f32 v[112:113], v[62:63], v[112:113] op_sel:[1,0] op_sel_hi:[1,1]
	v_pk_mul_f32 v[114:115], v[62:63], v[114:115] op_sel:[1,0] op_sel_hi:[1,1]
	v_pk_mul_f32 v[108:109], v[108:109], v[8:9]
	v_pk_mul_f32 v[110:111], v[110:111], v[10:11]
	v_pk_mul_f32 v[112:113], v[112:113], v[12:13]
	v_pk_mul_f32 v[114:115], v[114:115], v[14:15]
	global_store_dwordx4 v25, v[108:111], s[12:13] offset:2048
	global_store_dwordx4 v25, v[112:115], s[12:13] offset:2064
	s_add_u32 s12, s12, s16
	s_addc_u32 s13, s13, 0
	s_add_i32 s6, s6, s22
	s_cmp_lt_i32 s6, 0x8000
	s_cbranch_scc0 .Lfin_done
	s_branch .Lfin_loop
.Lfin_done:
.LBB0_1121:
	s_endpgm
